# v097 (packed S1 conv, B^T and G tiles) plus the S2 sum-of-squares adds packed into two v_pk_add_f32
# speedup vs baseline: 1.0074x; 1.0074x over previous
; #define LAS __attribute__((address_space(3)))
; __device__ __forceinline__ unsigned pk2(float lo, float hi) { unsigned r; asm("v_cvt_pk_bf16_f32 %0, %1, %2" : "=v"(r) : "v"(lo), "v"(hi)); return r; }
; __device__ __forceinline__ bf16_t f2bf(float f) { return (bf16_t)(pk2(f, 0.f) & 0xffffu); }
; __device__ __forceinline__ float bflo(unsigned w) { return __uint_as_float(w << 16); }
; __device__ __forceinline__ void ssd_item(const Args& a, LAS unsigned char* lds, int layer, bool is_sample, int b, int h, int seq_row0, int nchunks,
;                                          bf16_t* proj, float* ssq, const int tid) {
;     ...
;         {
;             float o[8];
; #pragma unroll
;             for (int i = 0; i < 8; ++i) o[i] = cb[i];
; #pragma unroll
;             for (int k = 0; k < 4; ++k) { const u32x4 w = *(const LAS u32x4*)(lds + L_XRAW + (lane + k) * P64 + wave * 16);
;                 o[0] += cw[k][0] * bflo(w.x); o[1] += cw[k][1] * bfhi(w.x); o[2] += cw[k][2] * bflo(w.y); o[3] += cw[k][3] * bfhi(w.y);
;                 o[4] += cw[k][4] * bflo(w.z); o[5] += cw[k][5] * bfhi(w.z); o[6] += cw[k][6] * bflo(w.w); o[7] += cw[k][7] * bfhi(w.w); }
; #pragma unroll
;             for (int i = 0; i < 8; ++i) *(LAS bf16_t*)(lds + L_XST + (wave * 8 + i) * P64 + lane * 2) = f2bf(siluf_(o[i]));
;         }
;         {
;             const int oc = tid & 15, tk = (tid >> 4) * 2;
;             const float a63s = acv[63]; const float wa = dtv[tk] * __builtin_amdgcn_exp2f(a63s - acv[tk]), wb = dtv[tk + 1] * __builtin_amdgcn_exp2f(a63s - acv[tk + 1]);
;             LAS unsigned char* d = lds + L_BWT + (oc * 8) * P64 + ((((tk >> 3) ^ ((oc >> 1) & 7)) << 4) | ((tk * 2) & 15));
;             *(LAS unsigned*)(d + 0 * P64) = pk2(bflo(bo0.x) * wa, bflo(bo1.x) * wb); *(LAS unsigned*)(d + 1 * P64) = pk2(bfhi(bo0.x) * wa, bfhi(bo1.x) * wb);
;             *(LAS unsigned*)(d + 2 * P64) = pk2(bflo(bo0.y) * wa, bflo(bo1.y) * wb); *(LAS unsigned*)(d + 3 * P64) = pk2(bfhi(bo0.y) * wa, bfhi(bo1.y) * wb);
;             *(LAS unsigned*)(d + 4 * P64) = pk2(bflo(bo0.z) * wa, bflo(bo1.z) * wb); *(LAS unsigned*)(d + 5 * P64) = pk2(bfhi(bo0.z) * wa, bfhi(bo1.z) * wb);
;             *(LAS unsigned*)(d + 6 * P64) = pk2(bflo(bo0.w) * wa, bflo(bo1.w) * wb); *(LAS unsigned*)(d + 7 * P64) = pk2(bfhi(bo0.w) * wa, bfhi(bo1.w) * wb);
;         }
.LBB0_570:
	ds_read_b128 v[176:179], v123
	ds_read_b128 v[180:183], v123 offset:144
	ds_read_b128 v[184:187], v123 offset:288
	ds_read_b128 v[188:191], v123 offset:432
	s_add_i32 s65, s15, 0
	s_add_i32 s65, s65, 0x1c73c
	v_add_u32_e32 v164, v110, v192
	v_add_u32_e32 v149, s15, v120
	v_add_u32_e32 v151, s15, v119
	v_mov_b32_e32 v148, s65
	v_add_u32_e32 v150, 0x1a640, v149
	v_add_u32_e32 v149, 0x1c640, v149
	v_add_u32_e32 v152, 0x1a640, v151
	v_add_u32_e32 v151, 0x1c640, v151
	ds_read_b32 v148, v148
	ds_read_b32 v150, v150
	ds_read_b32 v149, v149
	ds_read_b32 v152, v152
	ds_read_b32 v151, v151
	v_add_u32_e32 v165, s15, v117
	s_waitcnt lgkmcnt(8)
	v_lshlrev_b32_e32 v216, 16, v176
	v_and_b32_e32 v217, 0xffff0000, v176
	v_lshlrev_b32_e32 v218, 16, v177
	v_and_b32_e32 v219, 0xffff0000, v177
	v_lshlrev_b32_e32 v220, 16, v178
	v_and_b32_e32 v221, 0xffff0000, v178
	v_lshlrev_b32_e32 v222, 16, v179
	v_and_b32_e32 v223, 0xffff0000, v179
	v_pk_fma_f32 v[102:103], v[6:7], v[216:217], v[38:39]
	v_pk_fma_f32 v[156:157], v[8:9], v[218:219], v[40:41]
	v_pk_fma_f32 v[158:159], v[2:3], v[220:221], v[34:35]
	v_pk_fma_f32 v[160:161], v[4:5], v[222:223], v[36:37]
	s_waitcnt lgkmcnt(7)
	v_lshlrev_b32_e32 v216, 16, v180
	v_and_b32_e32 v217, 0xffff0000, v180
	v_lshlrev_b32_e32 v218, 16, v181
	v_and_b32_e32 v219, 0xffff0000, v181
	v_lshlrev_b32_e32 v220, 16, v182
	v_and_b32_e32 v221, 0xffff0000, v182
	v_lshlrev_b32_e32 v222, 16, v183
	v_and_b32_e32 v223, 0xffff0000, v183
	v_pk_fma_f32 v[102:103], v[10:11], v[216:217], v[102:103]
	v_pk_fma_f32 v[156:157], v[12:13], v[218:219], v[156:157]
	v_pk_fma_f32 v[158:159], v[14:15], v[220:221], v[158:159]
	v_pk_fma_f32 v[160:161], v[16:17], v[222:223], v[160:161]
	s_waitcnt lgkmcnt(6)
	v_lshlrev_b32_e32 v216, 16, v184
	v_and_b32_e32 v217, 0xffff0000, v184
	v_lshlrev_b32_e32 v218, 16, v185
	v_and_b32_e32 v219, 0xffff0000, v185
	v_lshlrev_b32_e32 v220, 16, v186
	v_and_b32_e32 v221, 0xffff0000, v186
	v_lshlrev_b32_e32 v222, 16, v187
	v_and_b32_e32 v223, 0xffff0000, v187
	v_pk_fma_f32 v[102:103], v[18:19], v[216:217], v[102:103]
	v_pk_fma_f32 v[156:157], v[20:21], v[218:219], v[156:157]
	v_pk_fma_f32 v[158:159], v[22:23], v[220:221], v[158:159]
	v_pk_fma_f32 v[160:161], v[24:25], v[222:223], v[160:161]
	s_waitcnt lgkmcnt(5)
	v_lshlrev_b32_e32 v216, 16, v188
	v_and_b32_e32 v217, 0xffff0000, v188
	v_lshlrev_b32_e32 v218, 16, v189
	v_and_b32_e32 v219, 0xffff0000, v189
	v_lshlrev_b32_e32 v220, 16, v190
	v_and_b32_e32 v221, 0xffff0000, v190
	v_lshlrev_b32_e32 v222, 16, v191
	v_and_b32_e32 v223, 0xffff0000, v191
	v_pk_fma_f32 v[102:103], v[26:27], v[216:217], v[102:103]
	v_pk_fma_f32 v[156:157], v[28:29], v[218:219], v[156:157]
	v_pk_fma_f32 v[158:159], v[30:31], v[220:221], v[158:159]
	v_pk_fma_f32 v[160:161], v[32:33], v[222:223], v[160:161]
	v_mul_f32_e32 v224, 0xbfb8aa3b, v102
	v_mul_f32_e32 v225, 0xbfb8aa3b, v103
	v_mul_f32_e32 v226, 0xbfb8aa3b, v156
	v_mul_f32_e32 v227, 0xbfb8aa3b, v157
	v_mul_f32_e32 v228, 0xbfb8aa3b, v158
	v_mul_f32_e32 v229, 0xbfb8aa3b, v159
	v_mul_f32_e32 v230, 0xbfb8aa3b, v160
	v_mul_f32_e32 v231, 0xbfb8aa3b, v161
	v_exp_f32_e32 v224, v224
	v_exp_f32_e32 v225, v225
	v_exp_f32_e32 v226, v226
	v_exp_f32_e32 v227, v227
	v_exp_f32_e32 v228, v228
	v_exp_f32_e32 v229, v229
	v_exp_f32_e32 v230, v230
	v_exp_f32_e32 v231, v231
	v_pk_add_f32 v[224:225], v[224:225], 1.0 op_sel_hi:[1,0]
	v_pk_add_f32 v[226:227], v[226:227], 1.0 op_sel_hi:[1,0]
	v_pk_add_f32 v[228:229], v[228:229], 1.0 op_sel_hi:[1,0]
	v_pk_add_f32 v[230:231], v[230:231], 1.0 op_sel_hi:[1,0]
	v_rcp_f32_e32 v224, v224
	v_rcp_f32_e32 v225, v225
	v_rcp_f32_e32 v226, v226
	v_rcp_f32_e32 v227, v227
	v_rcp_f32_e32 v228, v228
	v_rcp_f32_e32 v229, v229
	v_rcp_f32_e32 v230, v230
	v_rcp_f32_e32 v231, v231
	v_pk_mul_f32 v[102:103], v[102:103], v[224:225]
	v_pk_mul_f32 v[156:157], v[156:157], v[226:227]
	v_pk_mul_f32 v[158:159], v[158:159], v[228:229]
	v_pk_mul_f32 v[160:161], v[160:161], v[230:231]
	v_cvt_pk_bf16_f32 v232, v102, v103
	v_cvt_pk_bf16_f32 v233, v156, v157
	v_cvt_pk_bf16_f32 v234, v158, v159
	v_cvt_pk_bf16_f32 v235, v160, v161
	ds_write_b16 v124, v232
	ds_write_b16_d16_hi v124, v232 offset:144
	ds_write_b16 v124, v233 offset:288
	ds_write_b16_d16_hi v124, v233 offset:432
	ds_write_b16 v194, v234 offset:576
	ds_write_b16_d16_hi v194, v234 offset:720
	ds_write_b16 v194, v235 offset:864
	ds_write_b16_d16_hi v194, v235 offset:1008
	s_waitcnt lgkmcnt(12)
	s_waitcnt lgkmcnt(10)
	v_sub_f32_e32 v103, v148, v149
	s_waitcnt lgkmcnt(8)
	v_sub_f32_e32 v148, v148, v151
	v_exp_f32_e32 v103, v103
	v_exp_f32_e32 v148, v148
	v_mul_f32_e32 v102, v150, v103
	v_mul_f32_e32 v103, v152, v148
	v_add_u32_e32 v224, 0xd000, v125
	v_lshlrev_b32_e32 v216, 16, v58
	v_lshlrev_b32_e32 v217, 16, v62
	v_and_b32_e32 v218, 0xffff0000, v58
	v_and_b32_e32 v219, 0xffff0000, v62
	v_pk_mul_f32 v[216:217], v[102:103], v[216:217]
	v_pk_mul_f32 v[218:219], v[102:103], v[218:219]
	v_cvt_pk_bf16_f32 v220, v216, v217
	v_cvt_pk_bf16_f32 v221, v218, v219
	ds_write2_b32 v224, v220, v221 offset1:36
	v_lshlrev_b32_e32 v216, 16, v59
	v_lshlrev_b32_e32 v217, 16, v63
	v_and_b32_e32 v218, 0xffff0000, v59
	v_and_b32_e32 v219, 0xffff0000, v63
	v_pk_mul_f32 v[216:217], v[102:103], v[216:217]
	v_pk_mul_f32 v[218:219], v[102:103], v[218:219]
	v_cvt_pk_bf16_f32 v222, v216, v217
	v_cvt_pk_bf16_f32 v223, v218, v219
	ds_write2_b32 v224, v222, v223 offset0:72 offset1:108
	v_lshlrev_b32_e32 v216, 16, v60
	v_lshlrev_b32_e32 v217, 16, v64
	v_and_b32_e32 v218, 0xffff0000, v60
	v_and_b32_e32 v219, 0xffff0000, v64
	v_pk_mul_f32 v[216:217], v[102:103], v[216:217]
	v_pk_mul_f32 v[218:219], v[102:103], v[218:219]
	v_cvt_pk_bf16_f32 v220, v216, v217
	v_cvt_pk_bf16_f32 v221, v218, v219
	ds_write2_b32 v224, v220, v221 offset0:144 offset1:180
	v_lshlrev_b32_e32 v216, 16, v61
	v_lshlrev_b32_e32 v217, 16, v65
	v_and_b32_e32 v218, 0xffff0000, v61
	v_and_b32_e32 v219, 0xffff0000, v65
	v_pk_mul_f32 v[216:217], v[102:103], v[216:217]
	v_pk_mul_f32 v[218:219], v[102:103], v[218:219]
	v_cvt_pk_bf16_f32 v222, v216, v217
	v_cvt_pk_bf16_f32 v223, v218, v219
	ds_write2_b32 v224, v222, v223 offset0:216 offset1:252
	ds_read_b128 v[58:61], v164 offset:18432
	v_add_u32_e32 v102, v111, v192
	ds_read_b128 v[62:65], v102 offset:35840
	ds_read_b128 v[148:151], v164 offset:18496
	ds_read_b128 v[152:155], v164 offset:18624
	s_waitcnt lgkmcnt(2)
; #define LAS __attribute__((address_space(3)))
; __device__ __forceinline__ bf16_t f2bf(float f) { return (bf16_t)(pk2(f, 0.f) & 0xffffu); }
; __device__ __forceinline__ f32x4 mfma16(bf16x8 a, bf16x8 b, f32x4 c) { return __builtin_amdgcn_mfma_f32_16x16x32_bf16(a, b, c, 0, 0, 0); }
; #define LBAR() do { asm volatile("s_waitcnt lgkmcnt(0)" ::: "memory"); __builtin_amdgcn_s_barrier(); asm volatile("" ::: "memory"); } while (0)
; __device__ __forceinline__ void ssd_item(const Args& a, LAS unsigned char* lds, int layer, bool is_sample, int b, int h, int seq_row0, int nchunks,
;                                          bf16_t* proj, float* ssq, const int tid) {
;     ...
;         {
;             float al[4];
; #pragma unroll
;             for (int j = 0; j < 4; ++j) al[j] = acv[16 * rb + 4 * fq + j];
; #pragma unroll
;             for (int ci = 0; ci < 2; ++ci) { const int cbk = (wave & 1) * 2 + ci; f32x4 acc = (f32x4){0.f, 0.f, 0.f, 0.f};
; #pragma unroll
;                 for (int ks = 0; ks < 4; ++ks) { const bf16x8 av = *(const LAS bf16x8*)(lds + L_CM + (16 * rb + fr) * P128 + (32 * ks + 8 * fq) * 2);
;                     const bf16x8 bv = *(const LAS bf16x8*)(lds + L_BM + (16 * cbk + fr) * P128 + (32 * ks + 8 * fq) * 2); acc = mfma16(av, bv, acc); }
;                 const int s = 16 * cbk + fr; const float as = acv[s], ds = dtv[s];
; #pragma unroll
;                 for (int j = 0; j < 4; ++j) { const int l = 16 * rb + 4 * fq + j;
;                     const float gv = (s <= l) ? acc[j] * __builtin_amdgcn_exp2f(al[j] - as) * ds : 0.f;
;                     *(LAS bf16_t*)(lds + L_G + l * P64 + s * 2) = f2bf(gv); } }
;         }
;         LBAR();
;     ...
;             const float dec = __builtin_amdgcn_exp2f(acv[63]);
; #pragma unroll
;             for (int i = 0; i < 4; ++i) { st[i] = st[i] * dec;
; #pragma unroll
;                 for (int ks = 0; ks < 2; ++ks) { const bf16x8 av = *(const LAS bf16x8*)(lds + L_XST + (16 * pb + fr) * P64 + (32 * ks + 8 * fq) * 2);
;                     const bf16x8 bv = *(const LAS bf16x8*)(lds + L_BWT + (16 * (nb0 + i) + fr) * P64 + (((4 * ks + fq) ^ ((nb0 + i) & 7)) << 4)); st[i] = mfma16(bv, av, st[i]); } }
	v_mfma_f32_16x16x32_bf16 v[58:61], v[58:61], v[62:65], 0
	ds_read_b128 v[62:65], v164 offset:18560
	ds_read_b128 v[156:159], v102 offset:35904
	ds_read_b128 v[160:163], v102 offset:35968
	v_add_u32_e32 v103, s15, v118
	v_add_u32_e32 v103, 0x1c640, v103
	s_waitcnt lgkmcnt(1)
	v_mfma_f32_16x16x32_bf16 v[58:61], v[148:151], v[156:159], v[58:61]
	ds_read_b128 v[148:151], v103
	v_add_u32_e32 v157, 0x1a640, v165
	v_add_u32_e32 v158, 0x1c680, v165
	s_waitcnt lgkmcnt(1)
	v_mfma_f32_16x16x32_bf16 v[58:61], v[62:65], v[160:163], v[58:61]
	v_add_u32_e32 v62, 0x1c640, v165
	ds_read_b32 v156, v62
	ds_read_b128 v[62:65], v102 offset:36032
	ds_read_b32 v102, v157
	ds_read_b32 v169, v158
	s_waitcnt lgkmcnt(2)
	v_mfma_f32_16x16x32_bf16 v[58:61], v[152:155], v[62:65], v[58:61]
	v_pk_add_f32 v[216:217], v[148:149], v[156:157] op_sel_hi:[1,0] neg_lo:[0,1] neg_hi:[0,1]
	v_pk_add_f32 v[218:219], v[150:151], v[156:157] op_sel_hi:[1,0] neg_lo:[0,1] neg_hi:[0,1]
	v_exp_f32_e32 v216, v216
	v_exp_f32_e32 v217, v217
	v_exp_f32_e32 v218, v218
	v_exp_f32_e32 v219, v219
	v_add_u32_e32 v63, v112, v195
	s_nop 2
	v_pk_mul_f32 v[58:59], v[58:59], v[216:217]
	v_pk_mul_f32 v[60:61], v[60:61], v[218:219]
	s_waitcnt lgkmcnt(1)
	v_pk_mul_f32 v[58:59], v[102:103], v[58:59] op_sel_hi:[0,1]
	v_pk_mul_f32 v[60:61], v[102:103], v[60:61] op_sel_hi:[0,1]
	v_cndmask_b32_e64 v58, v58, 0, s[40:41]
	v_cndmask_b32_e64 v59, v59, 0, s[42:43]
	v_cndmask_b32_e64 v60, v60, 0, s[44:45]
	v_cndmask_b32_e64 v61, v61, 0, s[46:47]
	v_cvt_pk_bf16_f32 v58, v58, v59
	v_cvt_pk_bf16_f32 v60, v60, v61
	ds_write_b16 v63, v58 offset:9216
	ds_write_b16_d16_hi v63, v58 offset:9360
	ds_write_b16 v63, v60 offset:9504
	ds_write_b16_d16_hi v63, v60 offset:9648
	ds_read_b128 v[58:61], v164 offset:18432
	v_add_u32_e32 v102, v114, v192
	ds_read_b128 v[62:65], v164 offset:18496
	ds_read_b128 v[152:155], v102 offset:35840
	ds_read_b128 v[156:159], v102 offset:35904
	s_waitcnt lgkmcnt(1)
	v_mfma_f32_16x16x32_bf16 v[58:61], v[58:61], v[152:155], 0
	ds_read_b128 v[152:155], v164 offset:18560
	s_waitcnt lgkmcnt(1)
	v_mfma_f32_16x16x32_bf16 v[58:61], v[62:65], v[156:159], v[58:61]
	ds_read_b128 v[62:65], v102 offset:35968
	ds_read_b128 v[156:159], v164 offset:18624
	ds_read_b128 v[160:163], v102 offset:36032
	s_waitcnt lgkmcnt(2)
	v_mfma_f32_16x16x32_bf16 v[58:61], v[152:155], v[62:65], v[58:61]
	v_pk_add_f32 v[216:217], v[148:149], v[168:169] op_sel:[0,1] op_sel_hi:[1,1] neg_lo:[0,1] neg_hi:[0,1]
	v_pk_add_f32 v[218:219], v[150:151], v[168:169] op_sel:[0,1] op_sel_hi:[1,1] neg_lo:[0,1] neg_hi:[0,1]
	v_add_u32_e32 v62, 0x1a680, v165
	v_exp_f32_e32 v216, v216
	v_exp_f32_e32 v217, v217
	v_exp_f32_e32 v218, v218
	v_exp_f32_e32 v219, v219
	s_waitcnt lgkmcnt(0)
	v_mfma_f32_16x16x32_bf16 v[58:61], v[156:159], v[160:163], v[58:61]
	ds_read_b32 v62, v62
	v_add_u32_e32 v64, v115, v195
	s_nop 5
	v_pk_mul_f32 v[58:59], v[58:59], v[216:217]
	v_pk_mul_f32 v[60:61], v[60:61], v[218:219]
	s_waitcnt lgkmcnt(0)
	v_pk_mul_f32 v[58:59], v[62:63], v[58:59] op_sel_hi:[0,1]
	v_pk_mul_f32 v[60:61], v[62:63], v[60:61] op_sel_hi:[0,1]
	v_cndmask_b32_e64 v58, v58, 0, s[48:49]
	v_cndmask_b32_e64 v59, v59, 0, s[50:51]
	v_cndmask_b32_e64 v60, v60, 0, s[52:53]
	v_cndmask_b32_e64 v61, v61, 0, s[54:55]
	v_cvt_pk_bf16_f32 v58, v58, v59
	v_cvt_pk_bf16_f32 v60, v60, v61
	ds_write_b16 v64, v58 offset:9216
	ds_write_b16_d16_hi v64, v58 offset:9360
	ds_write_b16 v64, v60 offset:9504
	ds_write_b16_d16_hi v64, v60 offset:9648
	s_waitcnt lgkmcnt(0)
	s_barrier
	v_mov_b32_e32 v58, s65
	ds_read_b32 v102, v58
	ds_read_b128 v[148:151], v147
	ds_read_b128 v[176:179], v137 offset:53248
	ds_read_b128 v[180:183], v139 offset:53248
	ds_read_b128 v[184:187], v141 offset:53248
	ds_read_b128 v[188:191], v143 offset:53248
	ds_read_b128 v[152:155], v147 offset:64
	ds_read_b128 v[216:219], v138 offset:53248
	ds_read_b128 v[220:223], v140 offset:53248
	ds_read_b128 v[224:227], v142 offset:53248
	ds_read_b128 v[228:231], v144 offset:53248
	ds_read_b128 v[156:159], v147 offset:9216
	ds_read_b128 v[160:163], v147 offset:9280
	s_waitcnt lgkmcnt(12)
	v_exp_f32_e32 v102, v102
	s_nop 0
	v_pk_mul_f32 v[66:67], v[66:67], v[102:103] op_sel_hi:[1,0]
	v_pk_mul_f32 v[68:69], v[68:69], v[102:103] op_sel_hi:[1,0]
	v_pk_mul_f32 v[78:79], v[78:79], v[102:103] op_sel_hi:[1,0]
	v_pk_mul_f32 v[80:81], v[80:81], v[102:103] op_sel_hi:[1,0]
	v_pk_mul_f32 v[70:71], v[70:71], v[102:103] op_sel_hi:[1,0]
	v_pk_mul_f32 v[72:73], v[72:73], v[102:103] op_sel_hi:[1,0]
	v_pk_mul_f32 v[74:75], v[74:75], v[102:103] op_sel_hi:[1,0]
	v_pk_mul_f32 v[76:77], v[76:77], v[102:103] op_sel_hi:[1,0]
	s_waitcnt lgkmcnt(11)
	s_waitcnt lgkmcnt(10)
	v_mfma_f32_16x16x32_bf16 v[66:69], v[176:179], v[148:151], v[66:69]
	s_waitcnt lgkmcnt(9)
	v_mfma_f32_16x16x32_bf16 v[78:81], v[180:183], v[148:151], v[78:81]
	s_waitcnt lgkmcnt(8)
	v_mfma_f32_16x16x32_bf16 v[70:73], v[184:187], v[148:151], v[70:73]
	s_waitcnt lgkmcnt(7)
	v_mfma_f32_16x16x32_bf16 v[74:77], v[188:191], v[148:151], v[74:77]
	ds_read_b128 v[232:235], v164 offset:18432
	ds_read_b128 v[236:239], v164 offset:18496
	ds_read_b128 v[240:243], v164 offset:18560
	ds_read_b128 v[244:247], v164 offset:18624
	ds_read_b128 v[176:179], v127
	ds_read_b128 v[180:183], v127 offset:64
	ds_read_b128 v[184:187], v127 offset:128
	ds_read_b128 v[188:191], v127 offset:192
	s_waitcnt lgkmcnt(14)
	s_waitcnt lgkmcnt(13)
	v_mfma_f32_16x16x32_bf16 v[66:69], v[216:219], v[152:155], v[66:69]
	s_waitcnt lgkmcnt(12)
	v_mfma_f32_16x16x32_bf16 v[78:81], v[220:223], v[152:155], v[78:81]
	s_waitcnt lgkmcnt(11)
	v_mfma_f32_16x16x32_bf16 v[70:73], v[224:227], v[152:155], v[70:73]
	s_waitcnt lgkmcnt(10)
; #define LAS __attribute__((address_space(3)))
; __device__ __forceinline__ bf16_t f2bf(float f) { return (bf16_t)(pk2(f, 0.f) & 0xffffu); }
; __device__ __forceinline__ float bflo(unsigned w) { return __uint_as_float(w << 16); }
; __device__ __forceinline__ float bfhi(unsigned w) { return __uint_as_float(w & 0xffff0000u); }
; __device__ __forceinline__ void ssd_item(const Args& a, LAS unsigned char* lds, int layer, bool is_sample, int b, int h, int seq_row0, int nchunks,
;                                          bf16_t* proj, float* ssq, const int tid) {
;     ...
;             float sq[4] = {0.f, 0.f, 0.f, 0.f}, el[4];
; #pragma unroll
;             for (int j = 0; j < 4; ++j) el[j] = __builtin_amdgcn_exp2f(acv[16 * rb + 4 * fq + j]);
; #pragma unroll
;             for (int ci = 0; ci < 2; ++ci) { const int cbk = (wave & 1) * 2 + ci; f32x4 acc = (f32x4){0.f, 0.f, 0.f, 0.f}, acp = (f32x4){0.f, 0.f, 0.f, 0.f};
; #pragma unroll
;                 for (int ks = 0; ks < 2; ++ks) { const bf16x8 av = *(const LAS bf16x8*)(lds + L_G + (16 * rb + fr) * P64 + (32 * ks + 8 * fq) * 2);
;                     const bf16x8 bv = *(const LAS bf16x8*)(lds + L_XST + (16 * cbk + fr) * P64 + (32 * ks + 8 * fq) * 2); acc = mfma16(av, bv, acc); }
; #pragma unroll
;                 for (int ks = 0; ks < 4; ++ks) { const bf16x8 av = *(const LAS bf16x8*)(lds + L_CM + (16 * rb + fr) * P128 + (32 * ks + 8 * fq) * 2);
;                     const bf16x8 bv = *(const LAS bf16x8*)(lds + L_ST + (16 * cbk + fr) * P128 + (32 * ks + 8 * fq) * 2); acp = mfma16(av, bv, acp); }
;                 const int p = 16 * cbk + fr;
;                 const u32x2 xs4 = *(const LAS u32x2*)(lds + L_XST + p * P64 + (16 * rb + 4 * fq) * 2);
;                 const float xsv[4] = {bflo(xs4.x), bfhi(xs4.x), bflo(xs4.y), bfhi(xs4.y)};
; #pragma unroll
;                 for (int j = 0; j < 4; ++j) { const int l = 16 * rb + 4 * fq + j;
;                     LAS bf16_t* zp = (LAS bf16_t*)(lds + L_ZT + l * P64 + p * 2);
;                     const float z = bf2f(*zp);
;                     const float yg = (acc[j] + el[j] * acp[j] + xsv[j] * dsk) * siluf_(z);
;                     *zp = f2bf(yg); sq[j] += yg * yg; } }
; #pragma unroll
;             for (int j = 0; j < 4; ++j) { const float v = row16_sum(sq[j]);
;                 if (fr == 0) ssqp[(16 * rb + 4 * fq + j) * 2 + (wave & 1)] = v; }
	v_mfma_f32_16x16x32_bf16 v[74:77], v[228:231], v[152:155], v[74:77]
	ds_read_b128 v[148:151], v126
	ds_read_b128 v[152:155], v126 offset:64
	ds_read_b64 v[248:249], v128
	ds_read_b64 v[250:251], v128 offset:2304
	s_waitcnt lgkmcnt(7)
	v_mfma_f32_16x16x32_bf16 v[176:179], v[232:235], v[176:179], 0
	ds_read_b128 v[216:219], v131
	ds_read_b128 v[220:223], v131 offset:64
	ds_read_b128 v[224:227], v131 offset:128
	ds_read_b128 v[228:231], v131 offset:192
	ds_read_b128 v[58:61], v130
	ds_read_b128 v[62:65], v130 offset:64
	s_waitcnt lgkmcnt(12)
	v_mfma_f32_16x16x32_bf16 v[176:179], v[236:239], v[180:183], v[176:179]
	s_waitcnt lgkmcnt(11)
	v_mfma_f32_16x16x32_bf16 v[176:179], v[240:243], v[184:187], v[176:179]
	s_waitcnt lgkmcnt(10)
	v_mfma_f32_16x16x32_bf16 v[176:179], v[244:247], v[188:191], v[176:179]
	s_waitcnt lgkmcnt(9)
	v_mfma_f32_16x16x32_bf16 v[148:151], v[156:159], v[148:151], 0
	ds_read_u16 v165, v129
	ds_read_u16 v169, v129 offset:144
	ds_read_u16 v170, v129 offset:288
	ds_read_u16 v171, v129 offset:432
	s_waitcnt lgkmcnt(12)
	v_mfma_f32_16x16x32_bf16 v[148:151], v[160:163], v[152:155], v[148:151]
	s_waitcnt lgkmcnt(9)
	v_mfma_f32_16x16x32_bf16 v[216:219], v[232:235], v[216:219], 0
	ds_read_b128 v[232:235], v103
	ds_read_u16 v172, v132
	ds_read_u16 v173, v132 offset:144
	ds_read_u16 v215, v132 offset:288
	ds_read_u16 v102, v132 offset:432
	s_waitcnt lgkmcnt(13)
	v_mfma_f32_16x16x32_bf16 v[216:219], v[236:239], v[220:223], v[216:219]
	s_waitcnt lgkmcnt(10)
	v_mfma_f32_16x16x32_bf16 v[58:61], v[156:159], v[58:61], 0
	s_waitcnt lgkmcnt(9)
	v_mfma_f32_16x16x32_bf16 v[58:61], v[160:163], v[62:65], v[58:61]
	s_waitcnt lgkmcnt(4)
	v_exp_f32_e32 v232, v232
	v_exp_f32_e32 v233, v233
	v_exp_f32_e32 v234, v234
	v_exp_f32_e32 v235, v235
	v_mfma_f32_16x16x32_bf16 v[216:219], v[240:243], v[224:227], v[216:219]
	v_lshlrev_b32_e32 v180, 16, v248
	v_and_b32_e32 v181, 0xffff0000, v248
	v_lshlrev_b32_e32 v182, 16, v249
	v_and_b32_e32 v183, 0xffff0000, v249
	v_mfma_f32_16x16x32_bf16 v[216:219], v[244:247], v[228:231], v[216:219]
	v_lshlrev_b32_e32 v184, 16, v165
	v_lshlrev_b32_e32 v185, 16, v169
	v_lshlrev_b32_e32 v186, 16, v170
	v_lshlrev_b32_e32 v187, 16, v171
	v_mul_f32_e32 v188, 0xbfb8aa3b, v184
	v_mul_f32_e32 v189, 0xbfb8aa3b, v185
	v_mul_f32_e32 v190, 0xbfb8aa3b, v186
	v_mul_f32_e32 v191, 0xbfb8aa3b, v187
	v_exp_f32_e32 v188, v188
	v_exp_f32_e32 v189, v189
	v_exp_f32_e32 v190, v190
	v_exp_f32_e32 v191, v191
	v_pk_fma_f32 v[148:149], v[232:233], v[176:177], v[148:149]
	v_pk_fma_f32 v[150:151], v[234:235], v[178:179], v[150:151]
	v_pk_fma_f32 v[148:149], v[180:181], v[94:95], v[148:149] op_sel:[0,1,0] op_sel_hi:[1,1,1]
	v_pk_fma_f32 v[150:151], v[182:183], v[94:95], v[150:151] op_sel:[0,1,0] op_sel_hi:[1,1,1]
	v_pk_add_f32 v[188:189], v[188:189], 1.0 op_sel_hi:[1,0]
	v_pk_add_f32 v[190:191], v[190:191], 1.0 op_sel_hi:[1,0]
	v_rcp_f32_e32 v188, v188
	v_rcp_f32_e32 v189, v189
	v_rcp_f32_e32 v190, v190
	v_rcp_f32_e32 v191, v191
	v_pk_mul_f32 v[188:189], v[188:189], v[184:185]
	v_pk_mul_f32 v[190:191], v[190:191], v[186:187]
	v_pk_mul_f32 v[152:153], v[148:149], v[188:189]
	v_pk_mul_f32 v[154:155], v[150:151], v[190:191]
	v_cvt_pk_bf16_f32 v176, v152, v1
	ds_write_b16 v129, v176
	v_cvt_pk_bf16_f32 v177, v153, v1
	ds_write_b16 v129, v177 offset:144
	v_cvt_pk_bf16_f32 v178, v154, v1
	ds_write_b16 v129, v178 offset:288
	v_cvt_pk_bf16_f32 v179, v155, v1
	ds_write_b16 v129, v179 offset:432
	v_lshlrev_b32_e32 v184, 16, v250
	v_and_b32_e32 v185, 0xffff0000, v250
	v_lshlrev_b32_e32 v186, 16, v251
	v_and_b32_e32 v187, 0xffff0000, v251
	s_waitcnt lgkmcnt(7)
	v_lshlrev_b32_e32 v180, 16, v172
	s_waitcnt lgkmcnt(6)
	v_lshlrev_b32_e32 v181, 16, v173
	s_waitcnt lgkmcnt(5)
	v_lshlrev_b32_e32 v182, 16, v215
	s_waitcnt lgkmcnt(4)
	v_lshlrev_b32_e32 v183, 16, v102
	v_mul_f32_e32 v188, 0xbfb8aa3b, v180
	v_mul_f32_e32 v189, 0xbfb8aa3b, v181
	v_mul_f32_e32 v190, 0xbfb8aa3b, v182
	v_mul_f32_e32 v191, 0xbfb8aa3b, v183
	v_exp_f32_e32 v188, v188
	v_exp_f32_e32 v189, v189
	v_exp_f32_e32 v190, v190
	v_exp_f32_e32 v191, v191
	v_pk_fma_f32 v[58:59], v[232:233], v[216:217], v[58:59]
	v_pk_fma_f32 v[60:61], v[234:235], v[218:219], v[60:61]
	v_pk_fma_f32 v[58:59], v[184:185], v[94:95], v[58:59] op_sel:[0,1,0] op_sel_hi:[1,1,1]
	v_pk_fma_f32 v[60:61], v[186:187], v[94:95], v[60:61] op_sel:[0,1,0] op_sel_hi:[1,1,1]
	v_pk_add_f32 v[188:189], v[188:189], 1.0 op_sel_hi:[1,0]
	v_pk_add_f32 v[190:191], v[190:191], 1.0 op_sel_hi:[1,0]
	v_rcp_f32_e32 v188, v188
	v_rcp_f32_e32 v189, v189
	v_rcp_f32_e32 v190, v190
	v_rcp_f32_e32 v191, v191
	v_pk_mul_f32 v[188:189], v[188:189], v[180:181]
	v_pk_mul_f32 v[190:191], v[190:191], v[182:183]
	v_pk_mul_f32 v[62:63], v[58:59], v[188:189]
	v_pk_mul_f32 v[64:65], v[60:61], v[190:191]
	v_cvt_pk_bf16_f32 v220, v62, v1
	ds_write_b16 v132, v220
	v_cvt_pk_bf16_f32 v221, v63, v1
	ds_write_b16 v132, v221 offset:144
	v_cvt_pk_bf16_f32 v222, v64, v1
	ds_write_b16 v132, v222 offset:288
	v_cvt_pk_bf16_f32 v223, v65, v1
	ds_write_b16 v132, v223 offset:432
	v_pk_mul_f32 v[156:157], v[62:63], v[62:63]
	v_pk_mul_f32 v[158:159], v[64:65], v[64:65]
	v_pk_fma_f32 v[156:157], v[152:153], v[152:153], v[156:157]
	v_pk_fma_f32 v[158:159], v[154:155], v[154:155], v[158:159]
	s_nop 0
	v_add_f32_dpp v156, v156, v156 quad_perm:[1,0,3,2] row_mask:0xf bank_mask:0xf bound_ctrl:1
	v_add_f32_dpp v157, v157, v157 quad_perm:[1,0,3,2] row_mask:0xf bank_mask:0xf bound_ctrl:1
	v_add_f32_dpp v158, v158, v158 quad_perm:[1,0,3,2] row_mask:0xf bank_mask:0xf bound_ctrl:1
	v_add_f32_dpp v159, v159, v159 quad_perm:[1,0,3,2] row_mask:0xf bank_mask:0xf bound_ctrl:1
	v_add_f32_dpp v156, v156, v156 quad_perm:[2,3,0,1] row_mask:0xf bank_mask:0xf bound_ctrl:1
	v_add_f32_dpp v157, v157, v157 quad_perm:[2,3,0,1] row_mask:0xf bank_mask:0xf bound_ctrl:1
	v_add_f32_dpp v158, v158, v158 quad_perm:[2,3,0,1] row_mask:0xf bank_mask:0xf bound_ctrl:1
	v_add_f32_dpp v159, v159, v159 quad_perm:[2,3,0,1] row_mask:0xf bank_mask:0xf bound_ctrl:1
	v_add_f32_dpp v156, v156, v156 row_half_mirror row_mask:0xf bank_mask:0xf bound_ctrl:1
	v_add_f32_dpp v157, v157, v157 row_half_mirror row_mask:0xf bank_mask:0xf bound_ctrl:1
	v_add_f32_dpp v158, v158, v158 row_half_mirror row_mask:0xf bank_mask:0xf bound_ctrl:1
	v_add_f32_dpp v159, v159, v159 row_half_mirror row_mask:0xf bank_mask:0xf bound_ctrl:1
	v_mov_b32_dpp v160, v156 row_mirror row_mask:0xf bank_mask:0xf bound_ctrl:1
	v_mov_b32_dpp v161, v157 row_mirror row_mask:0xf bank_mask:0xf bound_ctrl:1
	v_mov_b32_dpp v162, v158 row_mirror row_mask:0xf bank_mask:0xf bound_ctrl:1
	v_mov_b32_dpp v163, v159 row_mirror row_mask:0xf bank_mask:0xf bound_ctrl:1
	s_and_saveexec_b64 s[20:21], s[6:7]
	v_pk_add_f32 v[156:157], v[156:157], v[160:161]
	v_pk_add_f32 v[158:159], v[158:159], v[162:163]
	ds_write_b32 v133, v156
	ds_write_b32 v134, v157
	ds_write_b32 v135, v158
	ds_write_b32 v136, v159
	s_or_b64 exec, exec, s[20:21]
	s_waitcnt lgkmcnt(0)
	s_barrier
; #define LAS __attribute__((address_space(3)))
; #define LBAR() do { asm volatile("s_waitcnt lgkmcnt(0)" ::: "memory"); __builtin_amdgcn_s_barrier(); asm volatile("" ::: "memory"); } while (0)
; __device__ __forceinline__ void ssd_item(const Args& a, LAS unsigned char* lds, int layer, bool is_sample, int b, int h, int seq_row0, int nchunks,
;                                          bf16_t* proj, float* ssq, const int tid) {
;     ...
;         LBAR();
;         if (tid < 64) ((LAS float*)(lds + L_SSQA))[c * 64 + tid] = ssqp[tid * 2] + ssqp[tid * 2 + 1];
	s_and_saveexec_b64 s[20:21], s[38:39]
	s_cbranch_execz .LBB0_560
	s_nop 1
	ds_read_b64 v[58:59], v145
	v_add_u32_e32 v60, s15, v116
	s_waitcnt lgkmcnt(0)
	v_add_f32_e32 v58, v58, v59
	ds_write_b32 v60, v58
	s_branch .LBB0_560
